# speedup vs baseline: 1.0784x; 1.0048x over previous
; DI unsigned pack2(float a, float b) { f32x2_t v = {a, b}; return __builtin_bit_cast(unsigned, __builtin_convertvector(v, bf16x2_t)); }
; DI void store_transposed(const f32x16& a00, const f32x16& a01, const f32x16& a10, const f32x16& a11, const float* rstd,
;                          bf16_t* dst  , size_t ldd, int r, int h) {
;   _Pragma("unroll") for (int mi = 0; mi < 2; ++mi) {
;     const f32x16& x0 = mi ? a10 : a00; const f32x16& x1 = mi ? a11 : a01;
;     _Pragma("unroll") for (int g = 0; g < 4; ++g) {
;       const int rl = mi * 32 + 8 * g + 4 * h;
;       float4 q = *(const float4*)(rstd + rl);
;       const float r0 = q.x, r1 = q.y, r2 = q.z, r3 = q.w;
;       u32x2 o;
;       o[0] = pack2(x0[4 * g] * r0, x0[4 * g + 1] * r1); o[1] = pack2(x0[4 * g + 2] * r2, x0[4 * g + 3] * r3);
;       *(u32x2*)(dst + (size_t)r * ldd + rl) = o;
;       o[0] = pack2(x1[4 * g] * r0, x1[4 * g + 1] * r1); o[1] = pack2(x1[4 * g + 2] * r2, x1[4 * g + 3] * r3);
;       *(u32x2*)(dst + (size_t)(32 + r) * ldd + rl) = o;
;     }
;   }
; }
.LBB0_495:
	s_or_b64 exec, exec, s[0:1]
	v_lshlrev_b32_e32 v132, 2, v128
	s_add_i32 s4, 0, 0x12000
	v_lshlrev_b32_e32 v133, 2, v160
	v_lshlrev_b32_e32 v135, 4, v160
	v_lshlrev_b32_e32 v134, 14, v161
	v_add3_u32 v164, s4, v132, v135
	v_or_b32_e32 v132, 8, v133
	v_or_b32_e32 v135, 16, v133
	v_or_b32_e32 v136, 24, v133
	v_or_b32_e32 v137, 32, v133
	v_or_b32_e32 v139, 40, v133
	v_or_b32_e32 v141, 48, v133
	v_or_b32_e32 v143, 56, v133
	v_ashrrev_i32_e32 v129, 31, v128
	v_cmp_ne_u32_e32 vcc, 0, v140
	v_lshlrev_b32_e32 v158, 1, v134
	v_lshlrev_b32_e32 v156, 1, v133
	v_lshlrev_b32_e32 v154, 1, v132
	v_lshlrev_b32_e32 v142, 1, v135
	v_lshlrev_b32_e32 v140, 1, v136
	v_lshlrev_b32_e32 v138, 1, v137
	v_lshlrev_b32_e32 v136, 1, v139
	v_lshlrev_b32_e32 v134, 1, v141
	v_lshlrev_b32_e32 v132, 1, v143
	v_lshlrev_b32_e32 v156, 4, v160
	v_or_b32_e32 v154, 8, v156
	v_or_b32_e32 v142, 32, v156
	v_or_b32_e32 v140, 40, v156
	v_or_b32_e32 v138, 64, v156
	v_or_b32_e32 v136, 0x48, v156
	v_or_b32_e32 v134, 0x60, v156
	v_or_b32_e32 v132, 0x68, v156
	s_waitcnt lgkmcnt(0)
	s_barrier
	s_and_saveexec_b64 s[0:1], vcc
	s_xor_b64 s[0:1], exec, s[0:1]
	s_cbranch_execz .LBB0_497
	v_readlane_b32 s80, v250, 10
	s_lshl_b32 s5, s3, 22
	v_readlane_b32 s90, v250, 20
	v_readlane_b32 s91, v250, 21
	s_add_u32 s5, s90, s5
	s_addc_u32 s7, s91, 0
	s_lshl_b32 s6, s2, 1
	s_add_u32 s6, s5, s6
	s_addc_u32 s7, s7, 0
	ds_read_b128 v[166:169], v164
	v_lshl_add_u64 v[170:171], v[128:129], 1, s[6:7]
	v_mov_b32_e32 v159, v153
	v_lshl_add_u64 v[174:175], v[170:171], 0, v[158:159]
	ds_read_b128 v[170:173], v164 offset:32
	s_mov_b64 s[6:7], 0x100000
	v_lshl_add_u64 v[176:177], v[174:175], 0, s[6:7]
	v_mov_b32_e32 v157, v153
	s_waitcnt lgkmcnt(1)
	v_pk_mul_f32 v[96:97], v[96:97], v[166:167]
	v_pk_mul_f32 v[98:99], v[98:99], v[168:169]
	v_cvt_pk_bf16_f32 v96, v96, v97
	v_cvt_pk_bf16_f32 v97, v98, v99
	v_lshl_add_u64 v[98:99], v[176:177], 0, v[156:157]
	v_pk_mul_f32 v[112:113], v[112:113], v[166:167]
	v_pk_mul_f32 v[114:115], v[114:115], v[168:169]
	global_store_dwordx2 v[98:99], v[96:97], off
	s_waitcnt lgkmcnt(0)
	v_pk_mul_f32 v[96:97], v[116:117], v[170:171]
	v_pk_mul_f32 v[98:99], v[118:119], v[172:173]
	v_cvt_pk_bf16_f32 v112, v112, v113
	v_cvt_pk_bf16_f32 v113, v114, v115
	v_lshl_add_u64 v[114:115], v[174:175], 0, v[156:157]
	v_cvt_pk_bf16_f32 v96, v96, v97
	v_cvt_pk_bf16_f32 v97, v98, v99
	global_store_dwordx2 v[114:115], v[96:97], off offset:8
	v_pk_mul_f32 v[96:97], v[100:101], v[170:171]
	v_mov_b32_e32 v155, v153
	v_cvt_pk_bf16_f32 v100, v96, v97
	v_pk_mul_f32 v[96:97], v[102:103], v[172:173]
	v_lshl_add_u64 v[102:103], v[176:177], 0, v[154:155]
	v_cvt_pk_bf16_f32 v101, v96, v97
	ds_read_b128 v[96:99], v164 offset:64
	global_store_dwordx2 v[102:103], v[100:101], off
	ds_read_b128 v[100:103], v164 offset:96
	global_store_dwordx2 v[114:115], v[112:113], off
	v_mov_b32_e32 v143, v153
	s_waitcnt lgkmcnt(1)
	v_pk_mul_f32 v[112:113], v[120:121], v[96:97]
	v_pk_mul_f32 v[116:117], v[122:123], v[98:99]
	v_pk_mul_f32 v[96:97], v[104:105], v[96:97]
	v_pk_mul_f32 v[98:99], v[106:107], v[98:99]
	v_cvt_pk_bf16_f32 v96, v96, v97
	v_cvt_pk_bf16_f32 v97, v98, v99
	v_lshl_add_u64 v[98:99], v[176:177], 0, v[142:143]
	global_store_dwordx2 v[98:99], v[96:97], off
	s_waitcnt lgkmcnt(0)
	v_pk_mul_f32 v[96:97], v[124:125], v[100:101]
	v_pk_mul_f32 v[98:99], v[126:127], v[102:103]
	v_cvt_pk_bf16_f32 v96, v96, v97
	v_cvt_pk_bf16_f32 v97, v98, v99
	global_store_dwordx2 v[114:115], v[96:97], off offset:40
	v_pk_mul_f32 v[96:97], v[108:109], v[100:101]
	v_mov_b32_e32 v141, v153
	v_cvt_pk_bf16_f32 v100, v96, v97
	v_pk_mul_f32 v[96:97], v[110:111], v[102:103]
	v_lshl_add_u64 v[102:103], v[176:177], 0, v[140:141]
	v_cvt_pk_bf16_f32 v101, v96, v97
	ds_read_b128 v[96:99], v164 offset:128
	global_store_dwordx2 v[102:103], v[100:101], off
	ds_read_b128 v[100:103], v164 offset:160
	v_mov_b32_e32 v139, v153
	v_mov_b32_e32 v137, v153
	s_waitcnt lgkmcnt(1)
	v_pk_mul_f32 v[64:65], v[64:65], v[96:97]
	v_pk_mul_f32 v[66:67], v[66:67], v[98:99]
	v_cvt_pk_bf16_f32 v64, v64, v65
	v_cvt_pk_bf16_f32 v65, v66, v67
	v_lshl_add_u64 v[66:67], v[176:177], 0, v[138:139]
	global_store_dwordx2 v[66:67], v[64:65], off
	s_waitcnt lgkmcnt(0)
	v_pk_mul_f32 v[64:65], v[84:85], v[100:101]
	v_pk_mul_f32 v[66:67], v[86:87], v[102:103]
	v_cvt_pk_bf16_f32 v64, v64, v65
	v_cvt_pk_bf16_f32 v65, v66, v67
	global_store_dwordx2 v[114:115], v[64:65], off offset:72
	v_pk_mul_f32 v[64:65], v[68:69], v[100:101]
	v_pk_mul_f32 v[80:81], v[80:81], v[96:97]
	v_cvt_pk_bf16_f32 v68, v64, v65
	v_pk_mul_f32 v[64:65], v[70:71], v[102:103]
	v_lshl_add_u64 v[70:71], v[176:177], 0, v[136:137]
	v_cvt_pk_bf16_f32 v69, v64, v65
	ds_read_b128 v[64:67], v164 offset:192
	global_store_dwordx2 v[70:71], v[68:69], off
	ds_read_b128 v[68:71], v164 offset:224
	v_pk_mul_f32 v[82:83], v[82:83], v[98:99]
	v_cvt_pk_bf16_f32 v80, v80, v81
	v_cvt_pk_bf16_f32 v81, v82, v83
	global_store_dwordx2 v[114:115], v[80:81], off offset:64
	s_waitcnt lgkmcnt(1)
	v_pk_mul_f32 v[80:81], v[88:89], v[64:65]
	v_pk_mul_f32 v[82:83], v[90:91], v[66:67]
	v_pk_mul_f32 v[64:65], v[72:73], v[64:65]
	v_pk_mul_f32 v[66:67], v[74:75], v[66:67]
	v_mov_b32_e32 v135, v153
	v_cvt_pk_bf16_f32 v64, v64, v65
	v_cvt_pk_bf16_f32 v65, v66, v67
	v_lshl_add_u64 v[66:67], v[176:177], 0, v[134:135]
	global_store_dwordx2 v[66:67], v[64:65], off
	s_waitcnt lgkmcnt(0)
	v_pk_mul_f32 v[64:65], v[92:93], v[68:69]
	v_pk_mul_f32 v[66:67], v[94:95], v[70:71]
	v_cvt_pk_bf16_f32 v64, v64, v65
	v_cvt_pk_bf16_f32 v65, v66, v67
	global_store_dwordx2 v[114:115], v[64:65], off offset:104
	v_pk_mul_f32 v[64:65], v[76:77], v[68:69]
	v_pk_mul_f32 v[66:67], v[78:79], v[70:71]
	v_mov_b32_e32 v133, v153
	v_cvt_pk_bf16_f32 v112, v112, v113
	v_cvt_pk_bf16_f32 v113, v116, v117
	v_cvt_pk_bf16_f32 v80, v80, v81
	v_cvt_pk_bf16_f32 v81, v82, v83
	v_cvt_pk_bf16_f32 v64, v64, v65
	v_cvt_pk_bf16_f32 v65, v66, v67
	v_lshl_add_u64 v[66:67], v[176:177], 0, v[132:133]
	v_readlane_b32 s81, v250, 11
	v_readlane_b32 s82, v250, 12
	v_readlane_b32 s83, v250, 13
	v_readlane_b32 s84, v250, 14
	v_readlane_b32 s85, v250, 15
	v_readlane_b32 s86, v250, 16
	v_readlane_b32 s87, v250, 17
	v_readlane_b32 s88, v250, 18
	v_readlane_b32 s89, v250, 19
	v_readlane_b32 s92, v250, 22
	v_readlane_b32 s93, v250, 23
	v_readlane_b32 s94, v250, 24
	v_readlane_b32 s95, v250, 25
	global_store_dwordx2 v[114:115], v[112:113], off offset:32
	global_store_dwordx2 v[114:115], v[80:81], off offset:96
	global_store_dwordx2 v[66:67], v[64:65], off

; DI unsigned pack2(float a, float b) { f32x2_t v = {a, b}; return __builtin_bit_cast(unsigned, __builtin_convertvector(v, bf16x2_t)); }
; DI void store_transposed(const f32x16& a00, const f32x16& a01, const f32x16& a10, const f32x16& a11, const float* rstd,
;                          bf16_t* dst  , size_t ldd, int r, int h) {
;   _Pragma("unroll") for (int mi = 0; mi < 2; ++mi) {
;     const f32x16& x0 = mi ? a10 : a00; const f32x16& x1 = mi ? a11 : a01;
;     _Pragma("unroll") for (int g = 0; g < 4; ++g) {
;       const int rl = mi * 32 + 8 * g + 4 * h;
;       float4 q = *(const float4*)(rstd + rl);
;       const float r0 = q.x, r1 = q.y, r2 = q.z, r3 = q.w;
;       u32x2 o;
;       o[0] = pack2(x0[4 * g] * r0, x0[4 * g + 1] * r1); o[1] = pack2(x0[4 * g + 2] * r2, x0[4 * g + 3] * r3);
;       *(u32x2*)(dst + (size_t)r * ldd + rl) = o;
;       o[0] = pack2(x1[4 * g] * r0, x1[4 * g + 1] * r1); o[1] = pack2(x1[4 * g + 2] * r2, x1[4 * g + 3] * r3);
;       *(u32x2*)(dst + (size_t)(32 + r) * ldd + rl) = o;
;     }
;   }
; }
.LBB0_502:
	s_or_b64 exec, exec, s[0:1]
	s_and_saveexec_b64 s[0:1], vcc
	s_xor_b64 s[0:1], exec, s[0:1]
	s_cbranch_execz .LBB0_504
	v_readlane_b32 s80, v250, 10
	s_lshl_b32 s3, s3, 22
	v_readlane_b32 s90, v250, 20
	v_readlane_b32 s91, v250, 21
	s_add_u32 s3, s90, s3
	s_addc_u32 s8, s91, 0
	s_lshl_b32 s2, s2, 1
	ds_read_b128 v[66:69], v164
	ds_read_b128 v[70:73], v164 offset:32
	s_add_u32 s2, s3, s2
	s_addc_u32 s3, s8, 0
	v_lshl_add_u64 v[64:65], v[128:129], 1, s[2:3]
	v_mov_b32_e32 v159, v153
	v_lshl_add_u64 v[74:75], v[64:65], 0, v[158:159]
	s_mov_b64 s[2:3], 0x300000
	v_lshl_add_u64 v[64:65], v[74:75], 0, s[2:3]
	v_mov_b32_e32 v157, v153
	s_waitcnt lgkmcnt(1)
	v_pk_mul_f32 v[32:33], v[32:33], v[66:67]
	v_pk_mul_f32 v[34:35], v[34:35], v[68:69]
	v_pk_mul_f32 v[48:49], v[48:49], v[66:67]
	v_pk_mul_f32 v[50:51], v[50:51], v[68:69]
	v_cvt_pk_bf16_f32 v32, v32, v33
	v_cvt_pk_bf16_f32 v33, v34, v35
	v_lshl_add_u64 v[34:35], v[64:65], 0, v[156:157]
	v_cvt_pk_bf16_f32 v48, v48, v49
	v_cvt_pk_bf16_f32 v49, v50, v51
	v_lshl_add_u64 v[50:51], v[74:75], 0, v[156:157]
	s_mov_b64 s[2:3], 0x200000
	global_store_dwordx2 v[34:35], v[32:33], off
	s_waitcnt lgkmcnt(0)
	v_pk_mul_f32 v[32:33], v[52:53], v[70:71]
	v_pk_mul_f32 v[34:35], v[54:55], v[72:73]
	v_lshl_add_u64 v[74:75], v[50:51], 0, s[2:3]
	v_cvt_pk_bf16_f32 v32, v32, v33
	v_cvt_pk_bf16_f32 v33, v34, v35
	global_store_dwordx2 v[74:75], v[32:33], off offset:8
	v_pk_mul_f32 v[32:33], v[36:37], v[70:71]
	v_mov_b32_e32 v155, v153
	v_cvt_pk_bf16_f32 v36, v32, v33
	v_pk_mul_f32 v[32:33], v[38:39], v[72:73]
	v_lshl_add_u64 v[38:39], v[64:65], 0, v[154:155]
	v_cvt_pk_bf16_f32 v37, v32, v33
	ds_read_b128 v[32:35], v164 offset:64
	s_mov_b32 s2, 0x200000
	global_store_dwordx2 v[38:39], v[36:37], off
	ds_read_b128 v[36:39], v164 offset:96
	v_add_co_u32_e32 v50, vcc, s2, v50
	v_mov_b32_e32 v143, v153
	s_nop 0
	v_addc_co_u32_e32 v51, vcc, 0, v51, vcc
	global_store_dwordx2 v[50:51], v[48:49], off
	s_waitcnt lgkmcnt(1)
	v_pk_mul_f32 v[48:49], v[56:57], v[32:33]
	v_pk_mul_f32 v[50:51], v[58:59], v[34:35]
	v_pk_mul_f32 v[32:33], v[40:41], v[32:33]
	v_pk_mul_f32 v[34:35], v[42:43], v[34:35]
	v_cvt_pk_bf16_f32 v32, v32, v33
	v_cvt_pk_bf16_f32 v33, v34, v35
	v_lshl_add_u64 v[34:35], v[64:65], 0, v[142:143]
	global_store_dwordx2 v[34:35], v[32:33], off
	s_waitcnt lgkmcnt(0)
	v_pk_mul_f32 v[32:33], v[60:61], v[36:37]
	v_pk_mul_f32 v[34:35], v[62:63], v[38:39]
	v_cvt_pk_bf16_f32 v32, v32, v33
	v_cvt_pk_bf16_f32 v33, v34, v35
	global_store_dwordx2 v[74:75], v[32:33], off offset:40
	v_pk_mul_f32 v[32:33], v[44:45], v[36:37]
	v_mov_b32_e32 v141, v153
	v_cvt_pk_bf16_f32 v36, v32, v33
	v_pk_mul_f32 v[32:33], v[46:47], v[38:39]
	v_lshl_add_u64 v[38:39], v[64:65], 0, v[140:141]
	v_cvt_pk_bf16_f32 v37, v32, v33
	ds_read_b128 v[32:35], v164 offset:128
	global_store_dwordx2 v[38:39], v[36:37], off
	ds_read_b128 v[36:39], v164 offset:160
	v_mov_b32_e32 v139, v153
	v_mov_b32_e32 v137, v153
	s_waitcnt lgkmcnt(1)
	v_pk_mul_f32 v[0:1], v[0:1], v[32:33]
	v_pk_mul_f32 v[2:3], v[2:3], v[34:35]
	v_cvt_pk_bf16_f32 v0, v0, v1
	v_cvt_pk_bf16_f32 v1, v2, v3
	v_lshl_add_u64 v[2:3], v[64:65], 0, v[138:139]
	global_store_dwordx2 v[2:3], v[0:1], off
	s_waitcnt lgkmcnt(0)
	v_pk_mul_f32 v[0:1], v[20:21], v[36:37]
	v_pk_mul_f32 v[2:3], v[22:23], v[38:39]
	v_cvt_pk_bf16_f32 v0, v0, v1
	v_cvt_pk_bf16_f32 v1, v2, v3
	global_store_dwordx2 v[74:75], v[0:1], off offset:72
	v_pk_mul_f32 v[0:1], v[4:5], v[36:37]
	v_pk_mul_f32 v[16:17], v[16:17], v[32:33]
	v_cvt_pk_bf16_f32 v4, v0, v1
	v_pk_mul_f32 v[0:1], v[6:7], v[38:39]
	v_lshl_add_u64 v[6:7], v[64:65], 0, v[136:137]
	v_cvt_pk_bf16_f32 v5, v0, v1
	ds_read_b128 v[0:3], v164 offset:192
	global_store_dwordx2 v[6:7], v[4:5], off
	ds_read_b128 v[4:7], v164 offset:224
	v_pk_mul_f32 v[18:19], v[18:19], v[34:35]
	v_cvt_pk_bf16_f32 v16, v16, v17
	v_cvt_pk_bf16_f32 v17, v18, v19
	global_store_dwordx2 v[74:75], v[16:17], off offset:64
	s_waitcnt lgkmcnt(1)
	v_pk_mul_f32 v[16:17], v[24:25], v[0:1]
	v_pk_mul_f32 v[18:19], v[26:27], v[2:3]
	v_pk_mul_f32 v[0:1], v[8:9], v[0:1]
	v_pk_mul_f32 v[2:3], v[10:11], v[2:3]
	v_mov_b32_e32 v135, v153
	v_cvt_pk_bf16_f32 v0, v0, v1
	v_cvt_pk_bf16_f32 v1, v2, v3
	v_lshl_add_u64 v[2:3], v[64:65], 0, v[134:135]
	global_store_dwordx2 v[2:3], v[0:1], off
	s_waitcnt lgkmcnt(0)
	v_pk_mul_f32 v[0:1], v[28:29], v[4:5]
	v_pk_mul_f32 v[2:3], v[30:31], v[6:7]
	v_cvt_pk_bf16_f32 v0, v0, v1
	v_cvt_pk_bf16_f32 v1, v2, v3
	global_store_dwordx2 v[74:75], v[0:1], off offset:104
	v_pk_mul_f32 v[0:1], v[12:13], v[4:5]
	v_pk_mul_f32 v[2:3], v[14:15], v[6:7]
	v_mov_b32_e32 v133, v153
	v_cvt_pk_bf16_f32 v48, v48, v49
	v_cvt_pk_bf16_f32 v49, v50, v51
	v_cvt_pk_bf16_f32 v16, v16, v17
	v_cvt_pk_bf16_f32 v17, v18, v19
	v_cvt_pk_bf16_f32 v0, v0, v1
	v_cvt_pk_bf16_f32 v1, v2, v3
	v_lshl_add_u64 v[2:3], v[64:65], 0, v[132:133]
	v_readlane_b32 s81, v250, 11
	v_readlane_b32 s82, v250, 12
	v_readlane_b32 s83, v250, 13
	v_readlane_b32 s84, v250, 14
	v_readlane_b32 s85, v250, 15
	v_readlane_b32 s86, v250, 16
	v_readlane_b32 s87, v250, 17
	v_readlane_b32 s88, v250, 18
	v_readlane_b32 s89, v250, 19
	v_readlane_b32 s92, v250, 22
	v_readlane_b32 s93, v250, 23
	v_readlane_b32 s94, v250, 24
	v_readlane_b32 s95, v250, 25
	global_store_dwordx2 v[74:75], v[48:49], off offset:32
	global_store_dwordx2 v[74:75], v[16:17], off offset:96
	global_store_dwordx2 v[2:3], v[0:1], off

; DI int tid_opaque() { int t = threadIdx.x; asm volatile("" : "+v"(t)); return t; }
; DI f32x16 zero16() { f32x16 z; _Pragma("unroll") for (int i = 0; i < 16; ++i) z[i] = 0.f; return z; }
; DI void attn_dma_k(const Params& P, int head, int tk0, char* smem, int stage, int w, int lane) {
;   _Pragma("unroll") for (int i = 0; i < 2; ++i) {
;     const int idx = w + 8 * i;
;     const int row = 4 * idx + (lane >> 4), pos = lane & 15;
;     const int c = pos ^ (row & 15);
;     const bf16_t* g = P.knope + (size_t)(tk0 + row) * 1024 + head * 128 + c * 8;
;     __builtin_amdgcn_global_load_lds((const unsigned*)g, (unsigned*)(smem + stage * 40960 + idx * 1024 + lane * 16), 16, 0, 0);
;   }
;   {
;     const int i = 0; (void)i;
;     const int idx = w;
;     const int row = 8 * idx + (lane >> 3), pos = lane & 7;
;     const int c = pos ^ ((row >> 1) & 7);
;     const bf16_t* g = P.kr + (size_t)(tk0 + row) * 64 + c * 8;
;     __builtin_amdgcn_global_load_lds((const unsigned*)g, (unsigned*)(smem + stage * 40960 + 16384 + idx * 1024 + lane * 16), 16, 0, 0);
;   }
; }
; DI void attn_item(const Params& P, int half, int item, char* smem) {
;   const int slen = half ? 16384 : 2048;
;   const int nqb = slen >> 8;
;   const int qb = item % nqb; const int head = (item / nqb) & 7; const int seq = item / (nqb * 8);
;   const int tid = tid_opaque(), lane = tid & 63, w = tid >> 6, r = lane & 31, h = lane >> 5;
;   const int qrow = seq * slen + qb * 256 + 32 * w + r;
;   bf16x8 qf[12];
;   _Pragma("unroll") for (int s = 0; s < 12; ++s)
;     qf[s] = *(const bf16x8*)(P.qfull + (size_t)qrow * 1536 + head * 192 + 16 * s + 8 * h);
;   f32x16 o[4]; o[0] = zero16(); o[1] = zero16(); o[2] = zero16(); o[3] = zero16();
;   float mrun = -1e30f, lrun = 0.f;
;   const int nkt = slen >> 6;
;   const int tkb = seq * slen;
;   const int rn = r & 15, rr8 = (r >> 1) & 7;
;   asm volatile("s_waitcnt vmcnt(0)" ::: "memory");
;   attn_dma_k(P, head, tkb, smem, 0, w, lane);
;   attn_dma_v(P, head, tkb, smem, 0, w, lane);
;   attn_dma_k(P, head, tkb + 64, smem, 1, w, lane);
;   attn_dma_v(P, head, tkb + 64, smem, 1, w, lane);
.LBB0_728:
	s_abs_i32 s11, s10
	s_mul_hi_u32 s12, s11, s8
	s_mul_i32 s13, s12, s7
	s_ashr_i32 s0, s10, 31
	s_sub_i32 s13, s11, s13
	s_xor_b32 s1, s0, s6
	s_add_i32 s14, s12, 1
	s_sub_i32 s15, s13, s7
	s_cmp_ge_u32 s13, s7
	s_cselect_b32 s12, s14, s12
	s_cselect_b32 s13, s15, s13
	s_add_i32 s14, s12, 1
	s_cmp_ge_u32 s13, s7
	s_cselect_b32 s12, s14, s12
	s_xor_b32 s12, s12, s1
	s_mul_hi_u32 s13, s11, s9
	s_sub_i32 s1, s12, s1
	s_mul_i32 s14, s13, s3
	s_mul_i32 s12, s1, s2
	s_sub_i32 s11, s11, s14
	s_sub_i32 s12, s10, s12
	s_and_b32 s1, s1, 7
	s_add_i32 s14, s13, 1
	s_sub_i32 s15, s11, s3
	s_cmp_ge_u32 s11, s3
	s_cselect_b32 s13, s14, s13
	s_cselect_b32 s11, s15, s11
	s_add_i32 s14, s13, 1
	s_cmp_ge_u32 s11, s3
	s_cselect_b32 s11, s14, s13
	s_xor_b32 s11, s11, s0
	s_sub_i32 s0, s11, s0
	v_mov_b32_e32 v16, v144
	s_lshl_b32 s0, s0, s4
	s_lshl_b32 s11, s12, 8
	s_add_i32 s11, s0, s11
	v_and_b32_e32 v17, 31, v16
	v_ashrrev_i32_e32 v4, 6, v16
	v_or_b32_e32 v0, s11, v17
	v_lshl_add_u32 v154, v4, 5, v0
	v_mov_b64_e32 v[0:1], s[18:19]
	s_movk_i32 s11, 0xc00
	v_readlane_b32 s14, v249, 0
	v_bfe_u32 v166, v16, 5, 1
	v_mad_i64_i32 v[0:1], s[12:13], v154, s11, v[0:1]
	v_readlane_b32 s15, v249, 1
	s_mul_i32 s14, s1, 0x180
	v_lshlrev_b32_e32 v152, 4, v166
	v_lshl_add_u64 v[0:1], v[0:1], 0, s[14:15]
	v_lshl_add_u64 v[0:1], v[0:1], 0, v[152:153]
	global_load_dwordx4 v[96:99], v[0:1], off
	global_load_dwordx4 v[100:103], v[0:1], off offset:32
	global_load_dwordx4 v[104:107], v[0:1], off offset:64
	global_load_dwordx4 v[108:111], v[0:1], off offset:96
	global_load_dwordx4 v[112:115], v[0:1], off offset:128
	global_load_dwordx4 v[116:119], v[0:1], off offset:160
	global_load_dwordx4 v[120:123], v[0:1], off offset:192
	global_load_dwordx4 v[124:127], v[0:1], off offset:224
	global_load_dwordx4 v[128:131], v[0:1], off offset:256
	global_load_dwordx4 v[132:135], v[0:1], off offset:288
	global_load_dwordx4 v[136:139], v[0:1], off offset:320
	global_load_dwordx4 v[140:143], v[0:1], off offset:352
	v_bfe_u32 v3, v16, 4, 2
	v_lshlrev_b32_e32 v0, 2, v4
	v_and_b32_e32 v2, 63, v16
	v_or_b32_e32 v169, v0, v3
	v_lshlrev_b32_e32 v168, 4, v2
	v_bitop3_b32 v2, v0, v16, v3 bitop3:0x36
	v_add_u32_e32 v0, s0, v169
	v_ashrrev_i32_e32 v1, 31, v0
	v_add_u32_e32 v5, 0, v168
	v_lshlrev_b64 v[0:1], 11, v[0:1]
	v_lshlrev_b32_e32 v170, 10, v4
	v_lshl_add_u64 v[0:1], s[20:21], 0, v[0:1]
	s_lshl_b32 s14, s1, 8
	v_lshlrev_b32_e32 v2, 4, v2
	v_add_u32_e32 v21, v5, v170
	s_lshl_b32 s11, s1, 7
	v_lshl_add_u64 v[0:1], v[0:1], 0, s[14:15]
	v_and_b32_e32 v152, 0xf0, v2
	v_readfirstlane_b32 s1, v21
	s_waitcnt vmcnt(0)
	v_lshl_add_u64 v[0:1], v[0:1], 0, v[152:153]
	s_mov_b32 m0, s1
	v_add_u32_e32 v8, 8, v4
	global_load_lds_dwordx4 v[0:1], off
	v_lshlrev_b32_e32 v0, 2, v8
	v_or_b32_e32 v22, v0, v3
	v_bitop3_b32 v2, v0, v16, v3 bitop3:0x36
	v_add_u32_e32 v0, s0, v22
	v_ashrrev_i32_e32 v1, 31, v0
	v_lshlrev_b64 v[0:1], 11, v[0:1]
	v_lshlrev_b32_e32 v171, 10, v8
	v_lshl_add_u64 v[0:1], s[20:21], 0, v[0:1]
	v_lshlrev_b32_e32 v2, 4, v2
	v_add_u32_e32 v23, v5, v171
	v_lshl_add_u64 v[0:1], v[0:1], 0, s[14:15]
	v_and_b32_e32 v2, 0xf0, v2
	v_mov_b32_e32 v3, v153
	v_readfirstlane_b32 s1, v23
	v_bfe_u32 v9, v16, 3, 3
	v_lshl_add_u64 v[0:1], v[0:1], 0, v[2:3]
	s_mov_b32 m0, s1
	v_lshl_or_b32 v172, v4, 3, v9
	global_load_lds_dwordx4 v[0:1], off
	v_lshrrev_b32_e32 v0, 1, v172
	v_xor_b32_e32 v4, v0, v16
	v_add_u32_e32 v0, s0, v172
	v_ashrrev_i32_e32 v1, 31, v0
	v_add3_u32 v24, 0, v170, v168
	v_lshlrev_b64 v[0:1], 7, v[0:1]
	v_lshlrev_b32_e32 v4, 4, v4
	v_add_u32_e32 v6, 0x4000, v24
	v_lshl_add_u64 v[0:1], s[50:51], 0, v[0:1]
	v_and_b32_e32 v4, 0x70, v4
	v_mov_b32_e32 v5, v153
	v_readfirstlane_b32 s1, v6
	v_lshl_add_u64 v[0:1], v[0:1], 0, v[4:5]
	s_mov_b32 m0, s1
	s_ashr_i32 s1, s0, 31
	global_load_lds_dwordx4 v[0:1], off
	v_add_u32_e32 v0, s11, v172
	v_ashrrev_i32_e32 v1, 31, v0
	v_lshlrev_b64 v[0:1], 15, v[0:1]
	v_lshl_add_u64 v[0:1], s[22:23], 0, v[0:1]
	s_lshl_b64 s[12:13], s[0:1], 1
	v_add_u32_e32 v10, 0x6000, v21
	v_lshl_add_u64 v[6:7], v[0:1], 0, s[12:13]
	v_readfirstlane_b32 s1, v10
	v_add_u32_e32 v14, 0x6000, v23
	v_lshl_add_u64 v[6:7], v[6:7], 0, v[4:5]
	s_mov_b32 m0, s1
	v_lshl_or_b32 v8, v8, 3, v9
	v_readfirstlane_b32 s1, v14
	global_load_lds_dwordx4 v[6:7], off
	v_lshrrev_b32_e32 v9, 1, v8
	v_add_u32_e32 v8, s11, v8
	s_mov_b32 m0, s1
	s_or_b32 s1, s0, 64
	v_xor_b32_e32 v12, v9, v16
	v_ashrrev_i32_e32 v9, 31, v8
	v_add_u32_e32 v14, s1, v169
	v_lshlrev_b64 v[8:9], 15, v[8:9]
	v_ashrrev_i32_e32 v15, 31, v14
	v_lshl_add_u64 v[8:9], s[22:23], 0, v[8:9]
	v_lshlrev_b32_e32 v12, 4, v12
	v_lshlrev_b64 v[14:15], 11, v[14:15]
	v_lshl_add_u64 v[10:11], v[8:9], 0, s[12:13]
	v_and_b32_e32 v12, 0x70, v12
	v_mov_b32_e32 v13, v153
	v_lshl_add_u64 v[14:15], s[20:21], 0, v[14:15]
	v_add_u32_e32 v21, 0xa000, v21
	v_lshl_add_u64 v[10:11], v[10:11], 0, v[12:13]
	v_lshl_add_u64 v[14:15], v[14:15], 0, s[14:15]
	v_readfirstlane_b32 s12, v21
; DI int tid_opaque() { int t = threadIdx.x; asm volatile("" : "+v"(t)); return t; }
; DI f32x16 zero16() { f32x16 z; _Pragma("unroll") for (int i = 0; i < 16; ++i) z[i] = 0.f; return z; }
; DI void attn_dma_v(const Params& P, int head, int tk0, char* smem, int vstage, int w, int lane) {
;   _Pragma("unroll") for (int i = 0; i < 2; ++i) {
;     const int idx = w + 8 * i;
;     const int row = 8 * idx + (lane >> 3), pos = lane & 7;
;     const int c = pos ^ ((row >> 1) & 7);
;     const bf16_t* g = P.vt + (size_t)(head * 128 + row) * TH + tk0 + c * 8;
;     __builtin_amdgcn_global_load_lds((const unsigned*)g, (unsigned*)(smem + vstage * 40960 + 24576 + idx * 1024 + lane * 16), 16, 0, 0);
;   }
; }
; DI void attn_item(const Params& P, int half, int item, char* smem) {
;   const int slen = half ? 16384 : 2048;
;   const int nqb = slen >> 8;
;   const int qb = item % nqb; const int head = (item / nqb) & 7; const int seq = item / (nqb * 8);
;   const int tid = tid_opaque(), lane = tid & 63, w = tid >> 6, r = lane & 31, h = lane >> 5;
;   const int qrow = seq * slen + qb * 256 + 32 * w + r;
;   bf16x8 qf[12];
;   _Pragma("unroll") for (int s = 0; s < 12; ++s)
;     qf[s] = *(const bf16x8*)(P.qfull + (size_t)qrow * 1536 + head * 192 + 16 * s + 8 * h);
;   f32x16 o[4]; o[0] = zero16(); o[1] = zero16(); o[2] = zero16(); o[3] = zero16();
;   float mrun = -1e30f, lrun = 0.f;
;   const int nkt = slen >> 6;
;   const int tkb = seq * slen;
;   const int rn = r & 15, rr8 = (r >> 1) & 7;
;   asm volatile("s_waitcnt vmcnt(0)" ::: "memory");
;   attn_dma_k(P, head, tkb, smem, 0, w, lane);
;   attn_dma_v(P, head, tkb, smem, 0, w, lane);
;   attn_dma_k(P, head, tkb + 64, smem, 1, w, lane);
;   attn_dma_v(P, head, tkb + 64, smem, 1, w, lane);
;   int cur = 0;
	global_load_lds_dwordx4 v[10:11], off
	v_lshl_add_u64 v[14:15], v[14:15], 0, v[152:153]
	s_mov_b32 m0, s12
	v_add_u32_e32 v21, 0xa000, v23
	global_load_lds_dwordx4 v[14:15], off
	v_add_u32_e32 v14, s1, v22
	v_ashrrev_i32_e32 v15, 31, v14
	v_lshlrev_b64 v[14:15], 11, v[14:15]
	v_lshl_add_u64 v[14:15], s[20:21], 0, v[14:15]
	v_lshl_add_u64 v[14:15], v[14:15], 0, s[14:15]
	v_readfirstlane_b32 s12, v21
	v_lshl_add_u64 v[14:15], v[14:15], 0, v[2:3]
	s_mov_b32 m0, s12
	v_add_u32_e32 v21, 0xe000, v24
	global_load_lds_dwordx4 v[14:15], off
	v_add_u32_e32 v14, s1, v172
	v_ashrrev_i32_e32 v15, 31, v14
	v_lshlrev_b64 v[14:15], 7, v[14:15]
	v_lshl_add_u64 v[14:15], s[50:51], 0, v[14:15]
	v_readfirstlane_b32 s1, v21
	v_lshl_add_u64 v[14:15], v[14:15], 0, v[4:5]
	s_mov_b32 m0, s1
	s_add_i32 s1, 0, 0x10000
	global_load_lds_dwordx4 v[14:15], off
	v_add_u32_e32 v14, s1, v168
	v_add_u32_e32 v15, v14, v170
	s_mov_b64 s[12:13], 0x80
	v_readfirstlane_b32 s1, v15
	v_lshl_add_u64 v[6:7], v[6:7], 0, s[12:13]
	s_mov_b32 m0, s1
	v_and_b32_e32 v18, 15, v16
	global_load_lds_dwordx4 v[6:7], off
	v_lshl_add_u64 v[6:7], v[10:11], 0, s[12:13]
	v_add_u32_e32 v10, v14, v171
	v_lshrrev_b32_e32 v19, 1, v16
	v_readfirstlane_b32 s1, v10
	s_mov_b32 m0, s1
	v_bfe_u32 v20, v16, 1, 3
	global_load_lds_dwordx4 v[6:7], off
	v_bitop3_b32 v6, v166, v16, 15 bitop3:0x78
	v_lshlrev_b32_e32 v175, 4, v6
	v_bitop3_b32 v6, v166, v18, 2 bitop3:0x36
	v_lshlrev_b32_e32 v176, 4, v6
	v_bitop3_b32 v6, v166, v18, 4 bitop3:0x36
	v_lshlrev_b32_e32 v177, 4, v6
	v_bitop3_b32 v6, v166, v18, 6 bitop3:0x36
	v_lshlrev_b32_e32 v178, 4, v6
	v_bitop3_b32 v6, v166, v18, 8 bitop3:0x36
	v_lshlrev_b32_e32 v179, 4, v6
	v_bitop3_b32 v6, v166, v18, 10 bitop3:0x36
	v_lshlrev_b32_e32 v180, 4, v6
	v_bitop3_b32 v6, v166, v18, 12 bitop3:0x36
	v_lshlrev_b32_e32 v181, 4, v6
	v_bitop3_b32 v6, v166, v18, 14 bitop3:0x36
	v_lshlrev_b32_e32 v182, 4, v6
	v_bitop3_b32 v6, v166, v19, 7 bitop3:0x78
	v_lshlrev_b32_e32 v183, 4, v6
	v_bitop3_b32 v6, v166, v20, 2 bitop3:0x36
	v_lshlrev_b32_e32 v184, 4, v6
	v_bitop3_b32 v6, v166, v20, 4 bitop3:0x36
	v_writelane_b32 v249, s14, 0
	s_add_u32 s12, s20, s14
	v_lshlrev_b32_e32 v185, 4, v6
	v_bitop3_b32 v6, v166, v20, 6 bitop3:0x36
	v_lshlrev_b32_e32 v187, 4, v20
	v_lshlrev_b32_e32 v252, 4, v166
	v_xor_b32_e32 v187, v187, v252
	s_addc_u32 s13, s21, 0
	v_mov_b32_e32 v64, 0
	v_ashrrev_i32_e32 v155, 31, v154
	v_mov_b32_e32 v167, 0
	v_lshlrev_b32_e32 v173, 8, v17
	v_lshlrev_b32_e32 v174, 7, v17
	v_lshlrev_b32_e32 v186, 4, v6
	v_xor_b32_e32 v188, 16, v187
	v_xor_b32_e32 v189, 32, v187
	v_xor_b32_e32 v190, 48, v187
	v_xor_b32_e32 v191, 64, v187
	v_xor_b32_e32 v192, 0x50, v187
	v_xor_b32_e32 v193, 0x60, v187
	v_xor_b32_e32 v194, 0x70, v187
	v_lshl_add_u64 v[156:157], s[12:13], 0, v[152:153]
	v_lshl_add_u64 v[158:159], s[12:13], 0, v[2:3]
	v_lshl_add_u64 v[160:161], s[50:51], 0, v[4:5]
	v_lshl_add_u64 v[162:163], v[0:1], 0, v[4:5]
	v_lshl_add_u64 v[164:165], v[8:9], 0, v[12:13]
	v_lshlrev_b32_e32 v252, 11, v169
	v_mov_b32_e32 v253, 0
	v_lshl_add_u64 v[156:157], v[156:157], 0, v[252:253]
	v_add_u32_e32 v252, 0x10000, v252
	v_readfirstlane_b32 s82, v170
	v_lshl_add_u64 v[158:159], v[158:159], 0, v[252:253]
	v_lshlrev_b32_e32 v252, 7, v172
	s_nop 0
	v_lshl_add_u64 v[160:161], v[160:161], 0, v[252:253]
	s_addk_i32 s0, 0x80
	s_mov_b32 s13, 0
	v_mov_b32_e32 v196, 0xf149f2ca
	s_mov_b32 s12, s5
	v_mov_b32_e32 v0, 0
	v_mov_b32_e32 v1, v64
	v_mov_b32_e32 v2, v64
	v_mov_b32_e32 v3, v64
	v_mov_b32_e32 v4, v64
	v_mov_b32_e32 v5, v64
	v_mov_b32_e32 v6, v64
	v_mov_b32_e32 v7, v64
	v_mov_b32_e32 v8, v64
	v_mov_b32_e32 v9, v64
	v_mov_b32_e32 v10, v64
	v_mov_b32_e32 v11, v64
	v_mov_b32_e32 v12, v64
	v_mov_b32_e32 v13, v64
	v_mov_b32_e32 v14, v64
	v_mov_b32_e32 v15, v64
	v_mov_b32_e32 v16, 0
	v_mov_b32_e32 v17, v64
	v_mov_b32_e32 v18, v64
	v_mov_b32_e32 v19, v64
	v_mov_b32_e32 v20, v64
	v_mov_b32_e32 v21, v64
	v_mov_b32_e32 v22, v64
	v_mov_b32_e32 v23, v64
	v_mov_b32_e32 v24, v64
	v_mov_b32_e32 v25, v64
	v_mov_b32_e32 v26, v64
	v_mov_b32_e32 v27, v64
	v_mov_b32_e32 v28, v64
	v_mov_b32_e32 v29, v64
	v_mov_b32_e32 v30, v64
	v_mov_b32_e32 v31, v64
	v_mov_b32_e32 v32, 0
	v_mov_b32_e32 v33, v64
	v_mov_b32_e32 v34, v64
	v_mov_b32_e32 v35, v64
	v_mov_b32_e32 v36, v64
	v_mov_b32_e32 v37, v64
	v_mov_b32_e32 v38, v64
	v_mov_b32_e32 v39, v64
	v_mov_b32_e32 v40, v64
	v_mov_b32_e32 v41, v64
	v_mov_b32_e32 v42, v64
	v_mov_b32_e32 v43, v64
	v_mov_b32_e32 v44, v64
	v_mov_b32_e32 v45, v64
	v_mov_b32_e32 v46, v64
	v_mov_b32_e32 v47, v64
	v_mov_b32_e32 v48, 0
	v_mov_b32_e32 v49, v64
	v_mov_b32_e32 v50, v64
	v_mov_b32_e32 v51, v64
	v_mov_b32_e32 v52, v64
	v_mov_b32_e32 v53, v64
	v_mov_b32_e32 v54, v64
	v_mov_b32_e32 v55, v64
	v_mov_b32_e32 v56, v64
	v_mov_b32_e32 v57, v64
	v_mov_b32_e32 v58, v64
	v_mov_b32_e32 v59, v64
	v_mov_b32_e32 v60, v64
	v_mov_b32_e32 v61, v64
	v_mov_b32_e32 v62, v64
	v_mov_b32_e32 v63, v64
	s_movk_i32 s17, 0x4000
	v_writelane_b32 v249, s15, 1
	s_waitcnt vmcnt(0)

; #define MFMA32(a, b, c) __builtin_amdgcn_mfma_f32_32x32x16_bf16((a), (b), (c), 0, 0, 0)
; DI void attn_item(const Params& P, int half, int item, char* smem) {
;     ...
;     _Pragma("unroll") for (int i = 0; i < 16; ++i) {
;       st[0][i] = __builtin_amdgcn_exp2f(st[0][i] - mnew); psum += st[0][i];
;       st[1][i] = __builtin_amdgcn_exp2f(st[1][i] - mnew); psum += st[1][i];
;     }
;     lrun = lrun * alpha + psum;
;     _Pragma("unroll") for (int mt = 0; mt < 4; ++mt) {
;       _Pragma("unroll") for (int i = 0; i < 16; ++i) o[mt][i] *= alpha;
;     }
;     const char* sv = smem + cur * 40960 + 24576;
;     _Pragma("unroll") for (int k2 = 0; k2 < 2; ++k2) {
;       _Pragma("unroll") for (int s2 = 0; s2 < 2; ++s2) {
;         bf16x8 pb = pack8(st[k2][8 * s2], st[k2][8 * s2 + 1], st[k2][8 * s2 + 2], st[k2][8 * s2 + 3],
;                           st[k2][8 * s2 + 4], st[k2][8 * s2 + 5], st[k2][8 * s2 + 6], st[k2][8 * s2 + 7]);
;         const int c0 = 4 * k2 + 2 * s2;
;         _Pragma("unroll") for (int mt = 0; mt < 4; ++mt) {
;           const char* vrow = sv + (32 * mt + r) * 128 + 8 * h;
;           s16x4 lo = *(const s16x4*)(vrow + ((c0 ^ rr8) << 4));
;           s16x4 hi = *(const s16x4*)(vrow + (((c0 + 1) ^ rr8) << 4));
;           bf16x8 va = __builtin_shufflevector(lo, hi, 0, 1, 2, 3, 4, 5, 6, 7);
;           o[mt] = MFMA32(va, pb, o[mt]);
;         }
;       }
;     }
;     cur = (cur == 2) ? 0 : cur + 1;
;   }
;   asm volatile("s_waitcnt vmcnt(0) lgkmcnt(0)" ::: "memory");
;   __syncthreads();
;   lrun += __shfl_xor(lrun, 32);
;   const float inv = 1.f / lrun;
;   _Pragma("unroll") for (int mt = 0; mt < 4; ++mt) {
;     _Pragma("unroll") for (int g = 0; g < 4; ++g) {
;       const int dv = 32 * mt + 8 * g + 4 * h;
;       const size_t off = (size_t)qrow * 1024 + head * 128 + dv;
.Lattn_norescale:
	v_cvt_pk_bf16_f32 v66, v80, v81
	v_add_f32_e32 v64, v65, v64
	v_add_f32_e32 v64, v82, v64
	v_add_f32_e32 v64, v207, v64
	v_add_f32_e32 v64, v83, v64
	v_cvt_pk_bf16_f32 v67, v82, v83
	v_add_u32_e32 v71, v205, v187
	ds_read_b128 v[72:75], v71 offset:24576
	ds_read_b128 v[76:79], v71 offset:28672
	ds_read_b128 v[252:255], v71 offset:32768
	ds_read_b128 v[80:83], v71 offset:36864
	v_add_f32_e32 v64, v208, v64
	v_add_f32_e32 v64, v84, v64
	v_add_f32_e32 v64, v209, v64
	v_add_f32_e32 v64, v68, v64
	v_add_f32_e32 v64, v85, v64
	v_add_f32_e32 v64, v69, v64
	v_add_f32_e32 v64, v86, v64
	v_add_f32_e32 v64, v70, v64
	v_cvt_pk_bf16_f32 v68, v84, v68
	v_cvt_pk_bf16_f32 v69, v69, v70
	v_add_f32_e32 v64, v87, v64
	s_waitcnt lgkmcnt(2)
	v_mfma_f32_32x32x16_bf16 v[48:63], v[72:75], v[66:69], v[48:63]
	v_mfma_f32_32x32x16_bf16 v[32:47], v[76:79], v[66:69], v[32:47]
	v_add_u32_e32 v71, v205, v189
	ds_read_b128 v[72:75], v71 offset:24576
	ds_read_b128 v[76:79], v71 offset:28672
	v_add_f32_e32 v64, v88, v64
	v_add_f32_e32 v64, v210, v64
	s_waitcnt lgkmcnt(2)
	v_mfma_f32_32x32x16_bf16 v[16:31], v[252:255], v[66:69], v[16:31]
	v_mfma_f32_32x32x16_bf16 v[0:15], v[80:83], v[66:69], v[0:15]
	v_cvt_pk_bf16_f32 v66, v88, v89
	v_cvt_pk_bf16_f32 v67, v90, v91
	v_cvt_pk_bf16_f32 v68, v92, v93
	v_cvt_pk_bf16_f32 v69, v94, v95
	ds_read_b128 v[252:255], v71 offset:32768
	ds_read_b128 v[80:83], v71 offset:36864
	v_add_f32_e32 v64, v89, v64
	v_add_f32_e32 v64, v211, v64
	s_waitcnt lgkmcnt(2)
	v_mfma_f32_32x32x16_bf16 v[48:63], v[72:75], v[66:69], v[48:63]
	v_mfma_f32_32x32x16_bf16 v[32:47], v[76:79], v[66:69], v[32:47]
	v_add_u32_e32 v71, v205, v191
	ds_read_b128 v[72:75], v71 offset:24576
	ds_read_b128 v[76:79], v71 offset:28672
	v_add_f32_e32 v64, v90, v64
	v_add_f32_e32 v64, v212, v64
	s_waitcnt lgkmcnt(2)
	v_mfma_f32_32x32x16_bf16 v[16:31], v[252:255], v[66:69], v[16:31]
	v_mfma_f32_32x32x16_bf16 v[0:15], v[80:83], v[66:69], v[0:15]
	v_cvt_pk_bf16_f32 v66, v206, v65
	v_cvt_pk_bf16_f32 v67, v207, v208
	v_cvt_pk_bf16_f32 v68, v209, v85
	v_cvt_pk_bf16_f32 v69, v86, v87
	ds_read_b128 v[252:255], v71 offset:32768
	ds_read_b128 v[80:83], v71 offset:36864
	v_add_f32_e32 v64, v91, v64
	v_add_f32_e32 v64, v213, v64
	s_waitcnt lgkmcnt(2)
	v_mfma_f32_32x32x16_bf16 v[48:63], v[72:75], v[66:69], v[48:63]
	v_mfma_f32_32x32x16_bf16 v[32:47], v[76:79], v[66:69], v[32:47]
	v_add_u32_e32 v71, v205, v193
	ds_read_b128 v[72:75], v71 offset:24576
	ds_read_b128 v[76:79], v71 offset:28672
	v_add_f32_e32 v64, v92, v64
	v_add_f32_e32 v64, v214, v64
	s_waitcnt lgkmcnt(2)
	v_mfma_f32_32x32x16_bf16 v[16:31], v[252:255], v[66:69], v[16:31]
	v_mfma_f32_32x32x16_bf16 v[0:15], v[80:83], v[66:69], v[0:15]
	v_cvt_pk_bf16_f32 v66, v210, v211
	v_cvt_pk_bf16_f32 v67, v212, v213
	v_cvt_pk_bf16_f32 v68, v214, v215
	v_cvt_pk_bf16_f32 v69, v216, v217
	ds_read_b128 v[252:255], v71 offset:32768
	ds_read_b128 v[80:83], v71 offset:36864
	v_add_f32_e32 v64, v93, v64
	v_add_f32_e32 v64, v215, v64
	v_add_f32_e32 v64, v94, v64
	v_add_f32_e32 v64, v216, v64
	v_add_f32_e32 v64, v95, v64
	v_add_f32_e32 v64, v217, v64
	v_fmac_f32_e32 v64, v197, v196
	v_mov_b32_e32 v196, v195
	s_waitcnt lgkmcnt(2)
	v_mfma_f32_32x32x16_bf16 v[48:63], v[72:75], v[66:69], v[48:63]
	v_mfma_f32_32x32x16_bf16 v[32:47], v[76:79], v[66:69], v[32:47]
	s_waitcnt lgkmcnt(0)
	v_mfma_f32_32x32x16_bf16 v[16:31], v[252:255], v[66:69], v[16:31]
	v_mfma_f32_32x32x16_bf16 v[0:15], v[80:83], v[66:69], v[0:15]
	s_cbranch_scc1 .LBB0_729
	ds_bpermute_b32 v65, v152, v64
	v_readlane_b32 s12, v250, 10
	v_readlane_b32 s13, v250, 11
	s_waitcnt vmcnt(0) lgkmcnt(0)
	s_waitcnt vmcnt(0) lgkmcnt(0)
	v_add_f32_e32 v64, v64, v65
	v_div_scale_f32 v65, s[0:1], v64, v64, 1.0
	v_rcp_f32_e32 v66, v65
	s_barrier
	s_add_i32 s10, s10, s74
	v_fma_f32 v67, -v65, v66, 1.0
	v_fmac_f32_e32 v66, v67, v66
	v_div_scale_f32 v67, vcc, 1.0, v64, 1.0
	v_mul_f32_e32 v68, v67, v66
	v_fma_f32 v69, -v65, v68, v67
	v_fmac_f32_e32 v68, v69, v66
	v_fma_f32 v65, -v65, v68, v67
	v_div_fmas_f32 v65, v65, v66, v68
	v_div_fixup_f32 v64, v65, v64, 1.0
	v_lshlrev_b32_e32 v65, 2, v166
	v_lshlrev_b64 v[66:67], 10, v[154:155]
	v_or3_b32 v66, s11, v65, v66
	v_lshlrev_b64 v[68:69], 1, v[66:67]
	v_lshl_add_u64 v[70:71], s[12:13], 0, v[68:69]
	global_load_dwordx2 v[70:71], v[70:71], off
	v_readlane_b32 s18, v250, 16
	v_readlane_b32 s19, v250, 17
	v_readlane_b32 s20, v250, 18
	v_readlane_b32 s21, v250, 19
	v_readlane_b32 s22, v250, 20
	v_readlane_b32 s23, v250, 21
	s_cmpk_gt_i32 s10, 0x1ff
	v_readlane_b32 s14, v250, 12
	v_readlane_b32 s15, v250, 13
	v_readlane_b32 s16, v250, 14
	v_readlane_b32 s17, v250, 15
	v_readlane_b32 s24, v250, 22
	v_readlane_b32 s25, v250, 23
	v_readlane_b32 s26, v250, 24
	v_readlane_b32 s27, v250, 25
	s_waitcnt vmcnt(0)
; DI unsigned pack2(float a, float b) { f32x2_t v = {a, b}; return __builtin_bit_cast(unsigned, __builtin_convertvector(v, bf16x2_t)); }
; DI float bflo(unsigned p) { return __uint_as_float(p << 16); }
; DI float bfhi(unsigned p) { return __uint_as_float(p & 0xffff0000u); }
; DI float siluf_(float x) { return x * frcp(1.f + __expf(-x)); }
; DI void attn_item(const Params& P, int half, int item, char* smem) {
;     ...
;   _Pragma("unroll") for (int mt = 0; mt < 4; ++mt) {
;     _Pragma("unroll") for (int g = 0; g < 4; ++g) {
;       const int dv = 32 * mt + 8 * g + 4 * h;
;       const size_t off = (size_t)qrow * 1024 + head * 128 + dv;
;       u32x2 gv = *(const u32x2*)(P.gb + off);
;       u32x2 ov;
;       ov[0] = pack2(o[mt][4 * g] * inv * siluf_(bflo(gv[0])), o[mt][4 * g + 1] * inv * siluf_(bfhi(gv[0])));
;       ov[1] = pack2(o[mt][4 * g + 2] * inv * siluf_(bflo(gv[1])), o[mt][4 * g + 3] * inv * siluf_(bfhi(gv[1])));
;       *(u32x2*)(P.mo + off) = ov;
;     }
;   }
	v_lshlrev_b32_e32 v72, 16, v70
	v_mul_f32_e32 v65, 0xbfb8aa3b, v72
	v_exp_f32_e32 v65, v65
	v_and_b32_e32 v73, 0xffff0000, v70
	v_lshlrev_b32_e32 v70, 16, v71
	v_and_b32_e32 v71, 0xffff0000, v71
	v_add_f32_e32 v65, 1.0, v65
	v_rcp_f32_e32 v74, v65
	v_pk_mul_f32 v[48:49], v[48:49], v[64:65] op_sel_hi:[1,0]
	v_mul_f32_e32 v65, 0xbfb8aa3b, v73
	v_exp_f32_e32 v65, v65
	s_nop 0
	v_add_f32_e32 v65, 1.0, v65
	v_rcp_f32_e32 v75, v65
	v_pk_mul_f32 v[50:51], v[50:51], v[64:65] op_sel_hi:[1,0]
	v_pk_mul_f32 v[52:53], v[52:53], v[64:65] op_sel_hi:[1,0]
	v_pk_mul_f32 v[54:55], v[54:55], v[64:65] op_sel_hi:[1,0]
	v_pk_mul_f32 v[72:73], v[74:75], v[72:73]
	v_pk_mul_f32 v[56:57], v[56:57], v[64:65] op_sel_hi:[1,0]
	v_pk_mul_f32 v[48:49], v[48:49], v[72:73]
	v_pk_mul_f32 v[32:33], v[32:33], v[64:65] op_sel_hi:[1,0]
	v_cvt_pk_bf16_f32 v48, v48, v49
	v_mul_f32_e32 v49, 0xbfb8aa3b, v70
	v_exp_f32_e32 v49, v49
	v_pk_mul_f32 v[34:35], v[34:35], v[64:65] op_sel_hi:[1,0]
	v_pk_mul_f32 v[36:37], v[36:37], v[64:65] op_sel_hi:[1,0]
	v_pk_mul_f32 v[38:39], v[38:39], v[64:65] op_sel_hi:[1,0]
	v_add_f32_e32 v49, 1.0, v49
	v_rcp_f32_e32 v72, v49
	v_mul_f32_e32 v49, 0xbfb8aa3b, v71
	v_exp_f32_e32 v49, v49
	v_pk_mul_f32 v[40:41], v[40:41], v[64:65] op_sel_hi:[1,0]
	v_pk_mul_f32 v[16:17], v[16:17], v[64:65] op_sel_hi:[1,0]
	v_pk_mul_f32 v[18:19], v[18:19], v[64:65] op_sel_hi:[1,0]
	v_add_f32_e32 v49, 1.0, v49
	v_rcp_f32_e32 v73, v49
	v_pk_mul_f32 v[20:21], v[20:21], v[64:65] op_sel_hi:[1,0]
	v_pk_mul_f32 v[22:23], v[22:23], v[64:65] op_sel_hi:[1,0]
	v_pk_mul_f32 v[24:25], v[24:25], v[64:65] op_sel_hi:[1,0]
	v_pk_mul_f32 v[70:71], v[72:73], v[70:71]
	v_pk_mul_f32 v[0:1], v[0:1], v[64:65] op_sel_hi:[1,0]
	v_pk_mul_f32 v[50:51], v[50:51], v[70:71]
	v_pk_mul_f32 v[2:3], v[2:3], v[64:65] op_sel_hi:[1,0]
	v_cvt_pk_bf16_f32 v49, v50, v51
	v_lshl_add_u64 v[50:51], s[58:59], 0, v[68:69]
	global_store_dwordx2 v[50:51], v[48:49], off
	v_or_b32_e32 v48, 8, v66
	v_mov_b32_e32 v49, v67
	v_lshlrev_b64 v[48:49], 1, v[48:49]
	v_lshl_add_u64 v[50:51], s[12:13], 0, v[48:49]
	global_load_dwordx2 v[50:51], v[50:51], off
	v_lshl_add_u64 v[48:49], s[58:59], 0, v[48:49]
	v_pk_mul_f32 v[4:5], v[4:5], v[64:65] op_sel_hi:[1,0]
	v_pk_mul_f32 v[6:7], v[6:7], v[64:65] op_sel_hi:[1,0]
	v_pk_mul_f32 v[8:9], v[8:9], v[64:65] op_sel_hi:[1,0]
	s_waitcnt vmcnt(0)
	v_lshlrev_b32_e32 v68, 16, v50
	v_and_b32_e32 v69, 0xffff0000, v50
	v_mul_f32_e32 v50, 0xbfb8aa3b, v68
	v_exp_f32_e32 v50, v50
	s_nop 0
	v_add_f32_e32 v50, 1.0, v50
	v_rcp_f32_e32 v70, v50
	v_mul_f32_e32 v50, 0xbfb8aa3b, v69
	v_exp_f32_e32 v50, v50
	s_nop 0
	v_add_f32_e32 v50, 1.0, v50
	v_rcp_f32_e32 v71, v50
	s_nop 0
	v_pk_mul_f32 v[68:69], v[70:71], v[68:69]
	s_nop 0
	v_pk_mul_f32 v[52:53], v[52:53], v[68:69]
	s_nop 0
	v_cvt_pk_bf16_f32 v50, v52, v53
	v_lshlrev_b32_e32 v52, 16, v51
	v_and_b32_e32 v53, 0xffff0000, v51
	v_mul_f32_e32 v51, 0xbfb8aa3b, v52
	v_exp_f32_e32 v51, v51
	s_nop 0
	v_add_f32_e32 v51, 1.0, v51
	v_rcp_f32_e32 v68, v51
	v_mul_f32_e32 v51, 0xbfb8aa3b, v53
	v_exp_f32_e32 v51, v51
	s_nop 0
	v_add_f32_e32 v51, 1.0, v51
	v_rcp_f32_e32 v69, v51
	s_nop 0
	v_pk_mul_f32 v[52:53], v[68:69], v[52:53]
	s_nop 0
	v_pk_mul_f32 v[52:53], v[54:55], v[52:53]
	s_nop 0
	v_cvt_pk_bf16_f32 v51, v52, v53
	global_store_dwordx2 v[48:49], v[50:51], off
	v_or_b32_e32 v48, 16, v66
	v_mov_b32_e32 v49, v67
	v_lshlrev_b64 v[48:49], 1, v[48:49]
	v_lshl_add_u64 v[50:51], s[12:13], 0, v[48:49]
	global_load_dwordx2 v[50:51], v[50:51], off
	v_lshl_add_u64 v[48:49], s[58:59], 0, v[48:49]
	s_waitcnt vmcnt(0)
	v_lshlrev_b32_e32 v52, 16, v50
	v_and_b32_e32 v53, 0xffff0000, v50
	v_mul_f32_e32 v50, 0xbfb8aa3b, v52
	v_exp_f32_e32 v50, v50
	s_nop 0
	v_add_f32_e32 v50, 1.0, v50
	v_rcp_f32_e32 v54, v50
	v_mul_f32_e32 v50, 0xbfb8aa3b, v53
	v_exp_f32_e32 v50, v50
	s_nop 0
	v_add_f32_e32 v50, 1.0, v50
	v_rcp_f32_e32 v55, v50
	s_nop 0
	v_pk_mul_f32 v[52:53], v[54:55], v[52:53]
	s_nop 0
	v_pk_mul_f32 v[52:53], v[56:57], v[52:53]
	v_pk_mul_f32 v[56:57], v[58:59], v[64:65] op_sel_hi:[1,0]
	v_cvt_pk_bf16_f32 v50, v52, v53
	v_lshlrev_b32_e32 v52, 16, v51
	v_and_b32_e32 v53, 0xffff0000, v51
	v_mul_f32_e32 v51, 0xbfb8aa3b, v52
	v_exp_f32_e32 v51, v51
	s_nop 0
	v_add_f32_e32 v51, 1.0, v51
	v_rcp_f32_e32 v54, v51
	v_mul_f32_e32 v51, 0xbfb8aa3b, v53
	v_exp_f32_e32 v51, v51
	s_nop 0
	v_add_f32_e32 v51, 1.0, v51
	v_rcp_f32_e32 v55, v51
	s_nop 0
	v_pk_mul_f32 v[52:53], v[54:55], v[52:53]
	s_nop 0
	v_pk_mul_f32 v[52:53], v[56:57], v[52:53]
	v_pk_mul_f32 v[56:57], v[60:61], v[64:65] op_sel_hi:[1,0]
	v_cvt_pk_bf16_f32 v51, v52, v53
	global_store_dwordx2 v[48:49], v[50:51], off
	v_or_b32_e32 v48, 24, v66
	v_mov_b32_e32 v49, v67
	v_lshlrev_b64 v[48:49], 1, v[48:49]
	v_lshl_add_u64 v[50:51], s[12:13], 0, v[48:49]
	global_load_dwordx2 v[50:51], v[50:51], off
	v_lshl_add_u64 v[48:49], s[58:59], 0, v[48:49]
	s_waitcnt vmcnt(0)
	v_lshlrev_b32_e32 v52, 16, v50
	v_and_b32_e32 v53, 0xffff0000, v50
	v_mul_f32_e32 v50, 0xbfb8aa3b, v52
	v_exp_f32_e32 v50, v50
	s_nop 0
	v_add_f32_e32 v50, 1.0, v50
	v_rcp_f32_e32 v54, v50
	v_mul_f32_e32 v50, 0xbfb8aa3b, v53
	v_exp_f32_e32 v50, v50
	s_nop 0
	v_add_f32_e32 v50, 1.0, v50
	v_rcp_f32_e32 v55, v50
	s_nop 0
	v_pk_mul_f32 v[52:53], v[54:55], v[52:53]
	s_nop 0
	v_pk_mul_f32 v[52:53], v[56:57], v[52:53]
	v_pk_mul_f32 v[56:57], v[62:63], v[64:65] op_sel_hi:[1,0]
	v_cvt_pk_bf16_f32 v50, v52, v53
	v_lshlrev_b32_e32 v52, 16, v51
	v_and_b32_e32 v53, 0xffff0000, v51
	v_mul_f32_e32 v51, 0xbfb8aa3b, v52
	v_exp_f32_e32 v51, v51
	s_nop 0
	v_add_f32_e32 v51, 1.0, v51
	v_rcp_f32_e32 v54, v51
	v_mul_f32_e32 v51, 0xbfb8aa3b, v53
	v_exp_f32_e32 v51, v51
	s_nop 0
	v_add_f32_e32 v51, 1.0, v51
	v_rcp_f32_e32 v55, v51
	s_nop 0
	v_pk_mul_f32 v[52:53], v[54:55], v[52:53]
	s_nop 0
	v_pk_mul_f32 v[52:53], v[56:57], v[52:53]
	s_nop 0
	v_cvt_pk_bf16_f32 v51, v52, v53
	global_store_dwordx2 v[48:49], v[50:51], off
	v_or_b32_e32 v48, 32, v66
	v_mov_b32_e32 v49, v67
	v_lshlrev_b64 v[48:49], 1, v[48:49]
	v_lshl_add_u64 v[50:51], s[12:13], 0, v[48:49]
	global_load_dwordx2 v[50:51], v[50:51], off
	s_waitcnt vmcnt(0)
; DI unsigned pack2(float a, float b) { f32x2_t v = {a, b}; return __builtin_bit_cast(unsigned, __builtin_convertvector(v, bf16x2_t)); }
; DI float bflo(unsigned p) { return __uint_as_float(p << 16); }
; DI float bfhi(unsigned p) { return __uint_as_float(p & 0xffff0000u); }
; DI float siluf_(float x) { return x * frcp(1.f + __expf(-x)); }
; DI void attn_item(const Params& P, int half, int item, char* smem) {
;     ...
;   _Pragma("unroll") for (int mt = 0; mt < 4; ++mt) {
;     _Pragma("unroll") for (int g = 0; g < 4; ++g) {
;       const int dv = 32 * mt + 8 * g + 4 * h;
;       const size_t off = (size_t)qrow * 1024 + head * 128 + dv;
;       u32x2 gv = *(const u32x2*)(P.gb + off);
;       u32x2 ov;
;       ov[0] = pack2(o[mt][4 * g] * inv * siluf_(bflo(gv[0])), o[mt][4 * g + 1] * inv * siluf_(bfhi(gv[0])));
;       ov[1] = pack2(o[mt][4 * g + 2] * inv * siluf_(bflo(gv[1])), o[mt][4 * g + 3] * inv * siluf_(bfhi(gv[1])));
;       *(u32x2*)(P.mo + off) = ov;
;     }
;   }
	v_lshlrev_b32_e32 v52, 16, v50
	v_and_b32_e32 v53, 0xffff0000, v50
	v_mul_f32_e32 v50, 0xbfb8aa3b, v52
	v_exp_f32_e32 v50, v50
	s_nop 0
	v_add_f32_e32 v50, 1.0, v50
	v_rcp_f32_e32 v54, v50
	v_mul_f32_e32 v50, 0xbfb8aa3b, v53
	v_exp_f32_e32 v50, v50
	s_nop 0
	v_add_f32_e32 v50, 1.0, v50
	v_rcp_f32_e32 v55, v50
	v_lshlrev_b32_e32 v50, 16, v51
	v_and_b32_e32 v51, 0xffff0000, v51
	v_pk_mul_f32 v[52:53], v[54:55], v[52:53]
	s_nop 0
	v_pk_mul_f32 v[32:33], v[32:33], v[52:53]
	s_nop 0
	v_cvt_pk_bf16_f32 v32, v32, v33
	v_mul_f32_e32 v33, 0xbfb8aa3b, v50
	v_exp_f32_e32 v33, v33
	s_nop 0
	v_add_f32_e32 v33, 1.0, v33
	v_rcp_f32_e32 v52, v33
	v_mul_f32_e32 v33, 0xbfb8aa3b, v51
	v_exp_f32_e32 v33, v33
	s_nop 0
	v_add_f32_e32 v33, 1.0, v33
	v_rcp_f32_e32 v53, v33
	s_nop 0
	v_pk_mul_f32 v[50:51], v[52:53], v[50:51]
	s_nop 0
	v_pk_mul_f32 v[34:35], v[34:35], v[50:51]
	s_nop 0
	v_cvt_pk_bf16_f32 v33, v34, v35
	v_lshl_add_u64 v[34:35], s[58:59], 0, v[48:49]
	global_store_dwordx2 v[34:35], v[32:33], off
	v_or_b32_e32 v32, 40, v66
	v_mov_b32_e32 v33, v67
	v_lshlrev_b64 v[32:33], 1, v[32:33]
	v_lshl_add_u64 v[34:35], s[12:13], 0, v[32:33]
	global_load_dwordx2 v[34:35], v[34:35], off
	v_lshl_add_u64 v[32:33], s[58:59], 0, v[32:33]
	s_waitcnt vmcnt(0)
	v_lshlrev_b32_e32 v48, 16, v34
	v_and_b32_e32 v49, 0xffff0000, v34
	v_mul_f32_e32 v34, 0xbfb8aa3b, v48
	v_exp_f32_e32 v34, v34
	s_nop 0
	v_add_f32_e32 v34, 1.0, v34
	v_rcp_f32_e32 v50, v34
	v_mul_f32_e32 v34, 0xbfb8aa3b, v49
	v_exp_f32_e32 v34, v34
	s_nop 0
	v_add_f32_e32 v34, 1.0, v34
	v_rcp_f32_e32 v51, v34
	s_nop 0
	v_pk_mul_f32 v[48:49], v[50:51], v[48:49]
	s_nop 0
	v_pk_mul_f32 v[36:37], v[36:37], v[48:49]
	s_nop 0
	v_cvt_pk_bf16_f32 v34, v36, v37
	v_lshlrev_b32_e32 v36, 16, v35
	v_and_b32_e32 v37, 0xffff0000, v35
	v_mul_f32_e32 v35, 0xbfb8aa3b, v36
	v_exp_f32_e32 v35, v35
	s_nop 0
	v_add_f32_e32 v35, 1.0, v35
	v_rcp_f32_e32 v48, v35
	v_mul_f32_e32 v35, 0xbfb8aa3b, v37
	v_exp_f32_e32 v35, v35
	s_nop 0
	v_add_f32_e32 v35, 1.0, v35
	v_rcp_f32_e32 v49, v35
	s_nop 0
	v_pk_mul_f32 v[36:37], v[48:49], v[36:37]
	s_nop 0
	v_pk_mul_f32 v[36:37], v[38:39], v[36:37]
	s_nop 0
	v_cvt_pk_bf16_f32 v35, v36, v37
	global_store_dwordx2 v[32:33], v[34:35], off
	v_or_b32_e32 v32, 48, v66
	v_mov_b32_e32 v33, v67
	v_lshlrev_b64 v[32:33], 1, v[32:33]
	v_lshl_add_u64 v[34:35], s[12:13], 0, v[32:33]
	global_load_dwordx2 v[34:35], v[34:35], off
	v_lshl_add_u64 v[32:33], s[58:59], 0, v[32:33]
	s_waitcnt vmcnt(0)
	v_lshlrev_b32_e32 v36, 16, v34
	v_and_b32_e32 v37, 0xffff0000, v34
	v_mul_f32_e32 v34, 0xbfb8aa3b, v36
	v_exp_f32_e32 v34, v34
	s_nop 0
	v_add_f32_e32 v34, 1.0, v34
	v_rcp_f32_e32 v38, v34
	v_mul_f32_e32 v34, 0xbfb8aa3b, v37
	v_exp_f32_e32 v34, v34
	s_nop 0
	v_add_f32_e32 v34, 1.0, v34
	v_rcp_f32_e32 v39, v34
	s_nop 0
	v_pk_mul_f32 v[36:37], v[38:39], v[36:37]
	s_nop 0
	v_pk_mul_f32 v[36:37], v[40:41], v[36:37]
	v_pk_mul_f32 v[40:41], v[42:43], v[64:65] op_sel_hi:[1,0]
	v_cvt_pk_bf16_f32 v34, v36, v37
	v_lshlrev_b32_e32 v36, 16, v35
	v_and_b32_e32 v37, 0xffff0000, v35
	v_mul_f32_e32 v35, 0xbfb8aa3b, v36
	v_exp_f32_e32 v35, v35
	s_nop 0
	v_add_f32_e32 v35, 1.0, v35
	v_rcp_f32_e32 v38, v35
	v_mul_f32_e32 v35, 0xbfb8aa3b, v37
	v_exp_f32_e32 v35, v35
	s_nop 0
	v_add_f32_e32 v35, 1.0, v35
	v_rcp_f32_e32 v39, v35
	s_nop 0
	v_pk_mul_f32 v[36:37], v[38:39], v[36:37]
	s_nop 0
	v_pk_mul_f32 v[36:37], v[40:41], v[36:37]
	v_pk_mul_f32 v[40:41], v[44:45], v[64:65] op_sel_hi:[1,0]
	v_cvt_pk_bf16_f32 v35, v36, v37
	global_store_dwordx2 v[32:33], v[34:35], off
	v_or_b32_e32 v32, 56, v66
	v_mov_b32_e32 v33, v67
	v_lshlrev_b64 v[32:33], 1, v[32:33]
	v_lshl_add_u64 v[34:35], s[12:13], 0, v[32:33]
	global_load_dwordx2 v[34:35], v[34:35], off
	v_lshl_add_u64 v[32:33], s[58:59], 0, v[32:33]
	s_waitcnt vmcnt(0)
	v_lshlrev_b32_e32 v36, 16, v34
	v_and_b32_e32 v37, 0xffff0000, v34
	v_mul_f32_e32 v34, 0xbfb8aa3b, v36
	v_exp_f32_e32 v34, v34
	s_nop 0
	v_add_f32_e32 v34, 1.0, v34
	v_rcp_f32_e32 v38, v34
	v_mul_f32_e32 v34, 0xbfb8aa3b, v37
	v_exp_f32_e32 v34, v34
	s_nop 0
	v_add_f32_e32 v34, 1.0, v34
	v_rcp_f32_e32 v39, v34
	s_nop 0
	v_pk_mul_f32 v[36:37], v[38:39], v[36:37]
	s_nop 0
	v_pk_mul_f32 v[36:37], v[40:41], v[36:37]
	v_pk_mul_f32 v[40:41], v[46:47], v[64:65] op_sel_hi:[1,0]
	v_cvt_pk_bf16_f32 v34, v36, v37
	v_lshlrev_b32_e32 v36, 16, v35
	v_and_b32_e32 v37, 0xffff0000, v35
	v_mul_f32_e32 v35, 0xbfb8aa3b, v36
	v_exp_f32_e32 v35, v35
	s_nop 0
	v_add_f32_e32 v35, 1.0, v35
	v_rcp_f32_e32 v38, v35
	v_mul_f32_e32 v35, 0xbfb8aa3b, v37
	v_exp_f32_e32 v35, v35
	s_nop 0
	v_add_f32_e32 v35, 1.0, v35
	v_rcp_f32_e32 v39, v35
	s_nop 0
	v_pk_mul_f32 v[36:37], v[38:39], v[36:37]
	s_nop 0
	v_pk_mul_f32 v[36:37], v[40:41], v[36:37]
	s_nop 0
	v_cvt_pk_bf16_f32 v35, v36, v37
	global_store_dwordx2 v[32:33], v[34:35], off
	v_or_b32_e32 v32, 64, v66
	v_mov_b32_e32 v33, v67
	v_lshlrev_b64 v[32:33], 1, v[32:33]
	v_lshl_add_u64 v[34:35], s[12:13], 0, v[32:33]
	global_load_dwordx2 v[34:35], v[34:35], off
	s_waitcnt vmcnt(0)
	v_lshlrev_b32_e32 v36, 16, v34
	v_and_b32_e32 v37, 0xffff0000, v34
	v_mul_f32_e32 v34, 0xbfb8aa3b, v36
	v_exp_f32_e32 v34, v34
	s_nop 0
	v_add_f32_e32 v34, 1.0, v34
	v_rcp_f32_e32 v38, v34
	v_mul_f32_e32 v34, 0xbfb8aa3b, v37
	v_exp_f32_e32 v34, v34
	s_nop 0
	v_add_f32_e32 v34, 1.0, v34
	v_rcp_f32_e32 v39, v34
	v_lshlrev_b32_e32 v34, 16, v35
	v_and_b32_e32 v35, 0xffff0000, v35
	v_pk_mul_f32 v[36:37], v[38:39], v[36:37]
	s_nop 0
	v_pk_mul_f32 v[16:17], v[16:17], v[36:37]
	s_nop 0
	v_cvt_pk_bf16_f32 v16, v16, v17
	v_mul_f32_e32 v17, 0xbfb8aa3b, v34
	v_exp_f32_e32 v17, v17
	s_nop 0
	v_add_f32_e32 v17, 1.0, v17
	v_rcp_f32_e32 v36, v17
	v_mul_f32_e32 v17, 0xbfb8aa3b, v35
	v_exp_f32_e32 v17, v17
	s_nop 0
	v_add_f32_e32 v17, 1.0, v17
	v_rcp_f32_e32 v37, v17
	s_nop 0
	v_pk_mul_f32 v[34:35], v[36:37], v[34:35]
	s_nop 0
	v_pk_mul_f32 v[18:19], v[18:19], v[34:35]
	s_nop 0
	v_cvt_pk_bf16_f32 v17, v18, v19
	v_lshl_add_u64 v[18:19], s[58:59], 0, v[32:33]
	global_store_dwordx2 v[18:19], v[16:17], off
	v_or_b32_e32 v16, 0x48, v66
	v_mov_b32_e32 v17, v67
	v_lshlrev_b64 v[16:17], 1, v[16:17]
	v_lshl_add_u64 v[18:19], s[12:13], 0, v[16:17]
	global_load_dwordx2 v[18:19], v[18:19], off
	v_lshl_add_u64 v[16:17], s[58:59], 0, v[16:17]
	s_waitcnt vmcnt(0)
; DI unsigned pack2(float a, float b) { f32x2_t v = {a, b}; return __builtin_bit_cast(unsigned, __builtin_convertvector(v, bf16x2_t)); }
; DI float bflo(unsigned p) { return __uint_as_float(p << 16); }
; DI float bfhi(unsigned p) { return __uint_as_float(p & 0xffff0000u); }
; DI float siluf_(float x) { return x * frcp(1.f + __expf(-x)); }
; DI void attn_item(const Params& P, int half, int item, char* smem) {
;     ...
;   _Pragma("unroll") for (int mt = 0; mt < 4; ++mt) {
;     _Pragma("unroll") for (int g = 0; g < 4; ++g) {
;       const int dv = 32 * mt + 8 * g + 4 * h;
;       const size_t off = (size_t)qrow * 1024 + head * 128 + dv;
;       u32x2 gv = *(const u32x2*)(P.gb + off);
;       u32x2 ov;
;       ov[0] = pack2(o[mt][4 * g] * inv * siluf_(bflo(gv[0])), o[mt][4 * g + 1] * inv * siluf_(bfhi(gv[0])));
;       ov[1] = pack2(o[mt][4 * g + 2] * inv * siluf_(bflo(gv[1])), o[mt][4 * g + 3] * inv * siluf_(bfhi(gv[1])));
;       *(u32x2*)(P.mo + off) = ov;
;     }
;   }
	v_lshlrev_b32_e32 v32, 16, v18
	v_and_b32_e32 v33, 0xffff0000, v18
	v_mul_f32_e32 v18, 0xbfb8aa3b, v32
	v_exp_f32_e32 v18, v18
	s_nop 0
	v_add_f32_e32 v18, 1.0, v18
	v_rcp_f32_e32 v34, v18
	v_mul_f32_e32 v18, 0xbfb8aa3b, v33
	v_exp_f32_e32 v18, v18
	s_nop 0
	v_add_f32_e32 v18, 1.0, v18
	v_rcp_f32_e32 v35, v18
	s_nop 0
	v_pk_mul_f32 v[32:33], v[34:35], v[32:33]
	s_nop 0
	v_pk_mul_f32 v[20:21], v[20:21], v[32:33]
	s_nop 0
	v_cvt_pk_bf16_f32 v18, v20, v21
	v_lshlrev_b32_e32 v20, 16, v19
	v_and_b32_e32 v21, 0xffff0000, v19
	v_mul_f32_e32 v19, 0xbfb8aa3b, v20
	v_exp_f32_e32 v19, v19
	s_nop 0
	v_add_f32_e32 v19, 1.0, v19
	v_rcp_f32_e32 v32, v19
	v_mul_f32_e32 v19, 0xbfb8aa3b, v21
	v_exp_f32_e32 v19, v19
	s_nop 0
	v_add_f32_e32 v19, 1.0, v19
	v_rcp_f32_e32 v33, v19
	s_nop 0
	v_pk_mul_f32 v[20:21], v[32:33], v[20:21]
	s_nop 0
	v_pk_mul_f32 v[20:21], v[22:23], v[20:21]
	s_nop 0
	v_cvt_pk_bf16_f32 v19, v20, v21
	global_store_dwordx2 v[16:17], v[18:19], off
	v_or_b32_e32 v16, 0x50, v66
	v_mov_b32_e32 v17, v67
	v_lshlrev_b64 v[16:17], 1, v[16:17]
	v_lshl_add_u64 v[18:19], s[12:13], 0, v[16:17]
	global_load_dwordx2 v[18:19], v[18:19], off
	v_lshl_add_u64 v[16:17], s[58:59], 0, v[16:17]
	s_waitcnt vmcnt(0)
	v_lshlrev_b32_e32 v20, 16, v18
	v_and_b32_e32 v21, 0xffff0000, v18
	v_mul_f32_e32 v18, 0xbfb8aa3b, v20
	v_exp_f32_e32 v18, v18
	s_nop 0
	v_add_f32_e32 v18, 1.0, v18
	v_rcp_f32_e32 v22, v18
	v_mul_f32_e32 v18, 0xbfb8aa3b, v21
	v_exp_f32_e32 v18, v18
	s_nop 0
	v_add_f32_e32 v18, 1.0, v18
	v_rcp_f32_e32 v23, v18
	s_nop 0
	v_pk_mul_f32 v[20:21], v[22:23], v[20:21]
	s_nop 0
	v_pk_mul_f32 v[20:21], v[24:25], v[20:21]
	v_pk_mul_f32 v[24:25], v[26:27], v[64:65] op_sel_hi:[1,0]
	v_cvt_pk_bf16_f32 v18, v20, v21
	v_lshlrev_b32_e32 v20, 16, v19
	v_and_b32_e32 v21, 0xffff0000, v19
	v_mul_f32_e32 v19, 0xbfb8aa3b, v20
	v_exp_f32_e32 v19, v19
	s_nop 0
	v_add_f32_e32 v19, 1.0, v19
	v_rcp_f32_e32 v22, v19
	v_mul_f32_e32 v19, 0xbfb8aa3b, v21
	v_exp_f32_e32 v19, v19
	s_nop 0
	v_add_f32_e32 v19, 1.0, v19
	v_rcp_f32_e32 v23, v19
	s_nop 0
	v_pk_mul_f32 v[20:21], v[22:23], v[20:21]
	s_nop 0
	v_pk_mul_f32 v[20:21], v[24:25], v[20:21]
	v_pk_mul_f32 v[24:25], v[28:29], v[64:65] op_sel_hi:[1,0]
	v_cvt_pk_bf16_f32 v19, v20, v21
	global_store_dwordx2 v[16:17], v[18:19], off
	v_or_b32_e32 v16, 0x58, v66
	v_mov_b32_e32 v17, v67
	v_lshlrev_b64 v[16:17], 1, v[16:17]
	v_lshl_add_u64 v[18:19], s[12:13], 0, v[16:17]
	global_load_dwordx2 v[18:19], v[18:19], off
	v_lshl_add_u64 v[16:17], s[58:59], 0, v[16:17]
	s_waitcnt vmcnt(0)
	v_lshlrev_b32_e32 v20, 16, v18
	v_and_b32_e32 v21, 0xffff0000, v18
	v_mul_f32_e32 v18, 0xbfb8aa3b, v20
	v_exp_f32_e32 v18, v18
	s_nop 0
	v_add_f32_e32 v18, 1.0, v18
	v_rcp_f32_e32 v22, v18
	v_mul_f32_e32 v18, 0xbfb8aa3b, v21
	v_exp_f32_e32 v18, v18
	s_nop 0
	v_add_f32_e32 v18, 1.0, v18
	v_rcp_f32_e32 v23, v18
	s_nop 0
	v_pk_mul_f32 v[20:21], v[22:23], v[20:21]
	s_nop 0
	v_pk_mul_f32 v[20:21], v[24:25], v[20:21]
	v_pk_mul_f32 v[24:25], v[30:31], v[64:65] op_sel_hi:[1,0]
	v_cvt_pk_bf16_f32 v18, v20, v21
	v_lshlrev_b32_e32 v20, 16, v19
	v_and_b32_e32 v21, 0xffff0000, v19
	v_mul_f32_e32 v19, 0xbfb8aa3b, v20
	v_exp_f32_e32 v19, v19
	s_nop 0
	v_add_f32_e32 v19, 1.0, v19
	v_rcp_f32_e32 v22, v19
	v_mul_f32_e32 v19, 0xbfb8aa3b, v21
	v_exp_f32_e32 v19, v19
	s_nop 0
	v_add_f32_e32 v19, 1.0, v19
	v_rcp_f32_e32 v23, v19
	s_nop 0
	v_pk_mul_f32 v[20:21], v[22:23], v[20:21]
	s_nop 0
	v_pk_mul_f32 v[20:21], v[24:25], v[20:21]
	s_nop 0
	v_cvt_pk_bf16_f32 v19, v20, v21
	global_store_dwordx2 v[16:17], v[18:19], off
	v_or_b32_e32 v16, 0x60, v66
	v_mov_b32_e32 v17, v67
	v_lshlrev_b64 v[16:17], 1, v[16:17]
	v_lshl_add_u64 v[18:19], s[12:13], 0, v[16:17]
	global_load_dwordx2 v[18:19], v[18:19], off
	s_waitcnt vmcnt(0)
; DI unsigned pack2(float a, float b) { f32x2_t v = {a, b}; return __builtin_bit_cast(unsigned, __builtin_convertvector(v, bf16x2_t)); }
; DI float bflo(unsigned p) { return __uint_as_float(p << 16); }
; DI float bfhi(unsigned p) { return __uint_as_float(p & 0xffff0000u); }
; DI float siluf_(float x) { return x * frcp(1.f + __expf(-x)); }
; DI void attn_item(const Params& P, int half, int item, char* smem) {
;     ...
;   _Pragma("unroll") for (int mt = 0; mt < 4; ++mt) {
;     _Pragma("unroll") for (int g = 0; g < 4; ++g) {
;       const int dv = 32 * mt + 8 * g + 4 * h;
;       const size_t off = (size_t)qrow * 1024 + head * 128 + dv;
;       u32x2 gv = *(const u32x2*)(P.gb + off);
;       u32x2 ov;
;       ov[0] = pack2(o[mt][4 * g] * inv * siluf_(bflo(gv[0])), o[mt][4 * g + 1] * inv * siluf_(bfhi(gv[0])));
;       ov[1] = pack2(o[mt][4 * g + 2] * inv * siluf_(bflo(gv[1])), o[mt][4 * g + 3] * inv * siluf_(bfhi(gv[1])));
;       *(u32x2*)(P.mo + off) = ov;
;     }
;   }
	v_lshlrev_b32_e32 v20, 16, v18
	v_and_b32_e32 v21, 0xffff0000, v18
	v_mul_f32_e32 v18, 0xbfb8aa3b, v20
	v_exp_f32_e32 v18, v18
	s_nop 0
	v_add_f32_e32 v18, 1.0, v18
	v_rcp_f32_e32 v22, v18
	v_mul_f32_e32 v18, 0xbfb8aa3b, v21
	v_exp_f32_e32 v18, v18
	s_nop 0
	v_add_f32_e32 v18, 1.0, v18
	v_rcp_f32_e32 v23, v18
	v_lshlrev_b32_e32 v18, 16, v19
	v_and_b32_e32 v19, 0xffff0000, v19
	v_pk_mul_f32 v[20:21], v[22:23], v[20:21]
	s_nop 0
	v_pk_mul_f32 v[0:1], v[0:1], v[20:21]
	s_nop 0
	v_cvt_pk_bf16_f32 v0, v0, v1
	v_mul_f32_e32 v1, 0xbfb8aa3b, v18
	v_exp_f32_e32 v1, v1
	s_nop 0
	v_add_f32_e32 v1, 1.0, v1
	v_rcp_f32_e32 v20, v1
	v_mul_f32_e32 v1, 0xbfb8aa3b, v19
	v_exp_f32_e32 v1, v1
	s_nop 0
	v_add_f32_e32 v1, 1.0, v1
	v_rcp_f32_e32 v21, v1
	s_nop 0
	v_pk_mul_f32 v[18:19], v[20:21], v[18:19]
	s_nop 0
	v_pk_mul_f32 v[2:3], v[2:3], v[18:19]
	s_nop 0
	v_cvt_pk_bf16_f32 v1, v2, v3
	v_lshl_add_u64 v[2:3], s[58:59], 0, v[16:17]
	global_store_dwordx2 v[2:3], v[0:1], off
	v_or_b32_e32 v0, 0x68, v66
	v_mov_b32_e32 v1, v67
	v_lshlrev_b64 v[0:1], 1, v[0:1]
	v_lshl_add_u64 v[2:3], s[12:13], 0, v[0:1]
	global_load_dwordx2 v[2:3], v[2:3], off
	v_lshl_add_u64 v[0:1], s[58:59], 0, v[0:1]
	s_waitcnt vmcnt(0)
	v_lshlrev_b32_e32 v16, 16, v2
	v_and_b32_e32 v17, 0xffff0000, v2
	v_mul_f32_e32 v2, 0xbfb8aa3b, v16
	v_exp_f32_e32 v2, v2
	s_nop 0
	v_add_f32_e32 v2, 1.0, v2
	v_rcp_f32_e32 v18, v2
	v_mul_f32_e32 v2, 0xbfb8aa3b, v17
	v_exp_f32_e32 v2, v2
	s_nop 0
	v_add_f32_e32 v2, 1.0, v2
	v_rcp_f32_e32 v19, v2
	s_nop 0
	v_pk_mul_f32 v[16:17], v[18:19], v[16:17]
	s_nop 0
	v_pk_mul_f32 v[4:5], v[4:5], v[16:17]
	s_nop 0
	v_cvt_pk_bf16_f32 v2, v4, v5
	v_lshlrev_b32_e32 v4, 16, v3
	v_and_b32_e32 v5, 0xffff0000, v3
	v_mul_f32_e32 v3, 0xbfb8aa3b, v4
	v_exp_f32_e32 v3, v3
	s_nop 0
	v_add_f32_e32 v3, 1.0, v3
	v_rcp_f32_e32 v16, v3
	v_mul_f32_e32 v3, 0xbfb8aa3b, v5
	v_exp_f32_e32 v3, v3
	s_nop 0
	v_add_f32_e32 v3, 1.0, v3
	v_rcp_f32_e32 v17, v3
	s_nop 0
	v_pk_mul_f32 v[4:5], v[16:17], v[4:5]
	s_nop 0
	v_pk_mul_f32 v[4:5], v[6:7], v[4:5]
	s_nop 0
	v_cvt_pk_bf16_f32 v3, v4, v5
	global_store_dwordx2 v[0:1], v[2:3], off
	v_or_b32_e32 v0, 0x70, v66
	v_mov_b32_e32 v1, v67
	v_lshlrev_b64 v[0:1], 1, v[0:1]
	v_lshl_add_u64 v[2:3], s[12:13], 0, v[0:1]
	global_load_dwordx2 v[2:3], v[2:3], off
	v_lshl_add_u64 v[0:1], s[58:59], 0, v[0:1]
	v_or_b32_e32 v66, 0x78, v66
	s_waitcnt vmcnt(0)
	v_lshlrev_b32_e32 v4, 16, v2
	v_and_b32_e32 v5, 0xffff0000, v2
	v_mul_f32_e32 v2, 0xbfb8aa3b, v4
	v_exp_f32_e32 v2, v2
	s_nop 0
	v_add_f32_e32 v2, 1.0, v2
	v_rcp_f32_e32 v6, v2
	v_mul_f32_e32 v2, 0xbfb8aa3b, v5
	v_exp_f32_e32 v2, v2
	s_nop 0
	v_add_f32_e32 v2, 1.0, v2
	v_rcp_f32_e32 v7, v2
	s_nop 0
	v_pk_mul_f32 v[4:5], v[6:7], v[4:5]
	s_nop 0
	v_pk_mul_f32 v[4:5], v[8:9], v[4:5]
	v_pk_mul_f32 v[8:9], v[10:11], v[64:65] op_sel_hi:[1,0]
	v_cvt_pk_bf16_f32 v2, v4, v5
	v_lshlrev_b32_e32 v4, 16, v3
	v_and_b32_e32 v5, 0xffff0000, v3
	v_mul_f32_e32 v3, 0xbfb8aa3b, v4
	v_exp_f32_e32 v3, v3
	s_nop 0
	v_add_f32_e32 v3, 1.0, v3
	v_rcp_f32_e32 v6, v3
	v_mul_f32_e32 v3, 0xbfb8aa3b, v5
	v_exp_f32_e32 v3, v3
	s_nop 0
	v_add_f32_e32 v3, 1.0, v3
	v_rcp_f32_e32 v7, v3
	s_nop 0
	v_pk_mul_f32 v[4:5], v[6:7], v[4:5]
	s_nop 0
	v_pk_mul_f32 v[4:5], v[8:9], v[4:5]
	v_pk_mul_f32 v[8:9], v[12:13], v[64:65] op_sel_hi:[1,0]
	v_cvt_pk_bf16_f32 v3, v4, v5
	global_store_dwordx2 v[0:1], v[2:3], off
	v_lshlrev_b64 v[0:1], 1, v[66:67]
	v_lshl_add_u64 v[2:3], s[12:13], 0, v[0:1]
	global_load_dwordx2 v[2:3], v[2:3], off
	v_lshl_add_u64 v[0:1], s[58:59], 0, v[0:1]
	s_waitcnt vmcnt(0)
	v_lshlrev_b32_e32 v4, 16, v2
	v_and_b32_e32 v5, 0xffff0000, v2
	v_mul_f32_e32 v2, 0xbfb8aa3b, v4
	v_exp_f32_e32 v2, v2
	s_nop 0
	v_add_f32_e32 v2, 1.0, v2
	v_rcp_f32_e32 v6, v2
	v_mul_f32_e32 v2, 0xbfb8aa3b, v5
	v_exp_f32_e32 v2, v2
	s_nop 0
	v_add_f32_e32 v2, 1.0, v2
	v_rcp_f32_e32 v7, v2
	s_nop 0
	v_pk_mul_f32 v[4:5], v[6:7], v[4:5]
	s_nop 0
	v_pk_mul_f32 v[4:5], v[8:9], v[4:5]
	v_pk_mul_f32 v[8:9], v[14:15], v[64:65] op_sel_hi:[1,0]
	v_cvt_pk_bf16_f32 v2, v4, v5
	v_lshlrev_b32_e32 v4, 16, v3
	v_and_b32_e32 v5, 0xffff0000, v3
	v_mul_f32_e32 v3, 0xbfb8aa3b, v4
	v_exp_f32_e32 v3, v3
	s_nop 0
	v_add_f32_e32 v3, 1.0, v3
	v_rcp_f32_e32 v6, v3
	v_mul_f32_e32 v3, 0xbfb8aa3b, v5
	v_exp_f32_e32 v3, v3
	s_nop 0
	v_add_f32_e32 v3, 1.0, v3
	v_rcp_f32_e32 v7, v3
	s_nop 0
	v_pk_mul_f32 v[4:5], v[6:7], v[4:5]
	s_nop 0
	v_pk_mul_f32 v[4:5], v[8:9], v[4:5]
	s_nop 0
	v_cvt_pk_bf16_f32 v3, v4, v5
	global_store_dwordx2 v[0:1], v[2:3], off
	s_cbranch_scc0 .LBB0_728
